# dpp
# speedup vs baseline: 1.0080x; 1.0034x over previous
; DEVI void ln_row(float (&x)[16], const float* __restrict__ g, const float* __restrict__ b, int lane, float* mu_out = nullptr,
;                  float* rstd_out = nullptr) {
;   float s = 0.f;
; #pragma unroll
;   for (int i = 0; i < 16; ++i) s += x[i];
;   s = wave_sum(s);
;   float mu = s * (1.0f / 1024.0f);
;   float v = 0.f;
; #pragma unroll
;   for (int i = 0; i < 16; ++i) { float d = x[i] - mu; v += d * d; }
;   v = wave_sum(v);
;   float rstd = rsqrtf(v * (1.0f / 1024.0f) + 1e-5f);
;   if (mu_out) { *mu_out = mu; *rstd_out = rstd; }
; DEVI void ph_lnrouter(const Params& p, int layer, char* shm) {
;     ...
;     const int tok = it * 8 + w;
;     float x[16];
; #pragma unroll
;     for (int i = 0; i < 4; ++i) {
;       float4 v = *reinterpret_cast<const float4*>(h32 + (size_t)tok * 1024 + i * 256 + lane * 4);
;       x[i * 4] = v.x; x[i * 4 + 1] = v.y; x[i * 4 + 2] = v.z; x[i * 4 + 3] = v.w;
;     }
;     float mu_, rstd_;
;     ln_row(x, g, b, lane, &mu_, &rstd_);
;     if (lane == 0) ((float2*)(p.ws + OFF_HB))[tok] = make_float2(mu_, rstd_);
.LBB0_1072:
	v_ashrrev_i32_e32 v55, 31, v54
	s_waitcnt lgkmcnt(0)
	v_lshlrev_b64 v[0:1], 12, v[54:55]
	v_lshl_add_u64 v[0:1], v[44:45], 0, v[0:1]
	global_load_dwordx4 v[24:27], v[0:1], off
	global_load_dwordx4 v[20:23], v[0:1], off offset:1024
	global_load_dwordx4 v[16:19], v[0:1], off offset:2048
	global_load_dwordx4 v[82:85], v[0:1], off offset:3072
	v_cmp_lt_i32_e32 vcc, v61, v60
	s_nop 1
	v_cndmask_b32_e32 v0, v59, v61, vcc
	v_lshlrev_b32_e32 v69, 2, v0
	v_cmp_lt_i32_e32 vcc, v62, v60
	s_waitcnt vmcnt(3)
	v_add_f32_e32 v0, 0, v24
	v_add_f32_e32 v0, v25, v0
	v_add_f32_e32 v0, v26, v0
	v_add_f32_e32 v0, v27, v0
	s_waitcnt vmcnt(2)
	v_add_f32_e32 v0, v20, v0
	v_add_f32_e32 v0, v21, v0
	v_add_f32_e32 v0, v22, v0
	v_add_f32_e32 v0, v23, v0
	s_waitcnt vmcnt(1)
	v_add_f32_e32 v0, v16, v0
	v_add_f32_e32 v0, v17, v0
	v_add_f32_e32 v0, v18, v0
	v_add_f32_e32 v0, v19, v0
	s_waitcnt vmcnt(0)
	v_add_f32_e32 v0, v82, v0
	v_add_f32_e32 v0, v83, v0
	v_add_f32_e32 v0, v84, v0
	v_add_f32_e32 v0, v85, v0
	ds_bpermute_b32 v1, v69, v0
	v_cndmask_b32_e32 v2, v59, v62, vcc
	v_lshlrev_b32_e32 v71, 2, v2
	v_cmp_lt_i32_e32 vcc, v63, v60
	s_waitcnt lgkmcnt(0)
	v_add_f32_e32 v0, v0, v1
	ds_bpermute_b32 v1, v71, v0
	v_cndmask_b32_e32 v2, v59, v63, vcc
	v_lshlrev_b32_e32 v70, 2, v2
	v_cmp_lt_i32_e32 vcc, v64, v60
	s_waitcnt lgkmcnt(0)
	v_add_f32_e32 v0, v0, v1
	s_nop 1
	v_mov_b32_dpp v1, v0 row_ror:8 row_mask:0xf bank_mask:0xf
	v_cndmask_b32_e32 v2, v59, v64, vcc
	v_lshlrev_b32_e32 v72, 2, v2
	v_cmp_lt_i32_e32 vcc, v65, v60
	s_waitcnt lgkmcnt(0)
	v_add_f32_e32 v0, v0, v1
	ds_bpermute_b32 v1, v72, v0
	v_cndmask_b32_e32 v3, v59, v65, vcc
	v_lshlrev_b32_e32 v74, 2, v3
	v_cmp_lt_i32_e32 vcc, v66, v60
	s_waitcnt lgkmcnt(0)
	v_add_f32_e32 v8, v0, v1
	s_nop 1
	v_mov_b32_dpp v9, v8 quad_perm:[2,3,0,1] row_mask:0xf bank_mask:0xf
	v_cndmask_b32_e32 v2, v59, v66, vcc
	v_lshlrev_b32_e32 v73, 2, v2
	global_load_dwordx4 v[40:43], v[46:47], off
	global_load_dwordx4 v[36:39], v[46:47], off offset:1024
	global_load_dwordx4 v[0:3], v[48:49], off
	global_load_dwordx4 v[4:7], v[48:49], off offset:1024
	s_waitcnt lgkmcnt(0)
	v_add_f32_e32 v56, v8, v9
	global_load_dwordx4 v[32:35], v[46:47], off offset:2048
	global_load_dwordx4 v[28:31], v[46:47], off offset:3072
	global_load_dwordx4 v[8:11], v[48:49], off offset:2048
	global_load_dwordx4 v[12:15], v[48:49], off offset:3072
	s_nop 1
	v_mov_b32_dpp v57, v56 quad_perm:[1,0,3,2] row_mask:0xf bank_mask:0xf
	s_waitcnt lgkmcnt(0)
	v_add_f32_e32 v57, v56, v57
	v_fmamk_f32 v79, v57, 0xba800000, v25
	v_fmamk_f32 v80, v57, 0xba800000, v24
	v_fmamk_f32 v24, v57, 0xba800000, v18
	v_mul_f32_e32 v18, v79, v79
	v_fmamk_f32 v78, v57, 0xba800000, v26
	v_fmac_f32_e32 v18, v80, v80
	v_fmac_f32_e32 v27, 0xba800000, v57
	v_fmac_f32_e32 v18, v78, v78
	v_fmamk_f32 v77, v57, 0xba800000, v20
	v_fmac_f32_e32 v18, v27, v27
	v_fmamk_f32 v76, v57, 0xba800000, v21
	v_fmac_f32_e32 v18, v77, v77
	v_fmamk_f32 v75, v57, 0xba800000, v22
	v_fmac_f32_e32 v18, v76, v76
	v_fmac_f32_e32 v23, 0xba800000, v57
	v_fmac_f32_e32 v18, v75, v75
	v_fmamk_f32 v26, v57, 0xba800000, v16
	v_fmac_f32_e32 v18, v23, v23
	v_fmamk_f32 v25, v57, 0xba800000, v17
	v_fmac_f32_e32 v18, v26, v26
	v_mul_f32_e32 v56, 0x3a800000, v57
	v_fmac_f32_e32 v18, v25, v25
	v_fmac_f32_e32 v19, 0xba800000, v57
	v_pk_add_f32 v[20:21], v[82:83], v[56:57] op_sel_hi:[1,0] neg_lo:[0,1] neg_hi:[0,1]
	v_fmac_f32_e32 v18, v24, v24
	v_pk_mul_f32 v[82:83], v[20:21], v[20:21]
	v_fmac_f32_e32 v18, v19, v19
	v_pk_add_f32 v[16:17], v[84:85], v[56:57] op_sel_hi:[1,0] neg_lo:[0,1] neg_hi:[0,1]
	v_add_f32_e32 v18, v82, v18
	v_pk_mul_f32 v[84:85], v[16:17], v[16:17]
	v_add_f32_e32 v18, v83, v18
	v_add_f32_e32 v18, v84, v18
	v_add_f32_e32 v18, v85, v18
	ds_bpermute_b32 v22, v69, v18
	s_waitcnt lgkmcnt(0)
	v_add_f32_e32 v18, v18, v22
	ds_bpermute_b32 v22, v71, v18
	s_waitcnt lgkmcnt(0)
	v_add_f32_e32 v18, v18, v22
	s_nop 1
	v_mov_b32_dpp v22, v18 row_ror:8 row_mask:0xf bank_mask:0xf
	s_waitcnt lgkmcnt(0)
	v_add_f32_e32 v18, v18, v22
	ds_bpermute_b32 v22, v72, v18
	s_waitcnt lgkmcnt(0)
	v_add_f32_e32 v18, v18, v22
	s_nop 1
	v_mov_b32_dpp v22, v18 quad_perm:[2,3,0,1] row_mask:0xf bank_mask:0xf
	s_waitcnt lgkmcnt(0)
	v_add_f32_e32 v18, v18, v22
	s_nop 1
	v_mov_b32_dpp v22, v18 quad_perm:[1,0,3,2] row_mask:0xf bank_mask:0xf
	s_waitcnt lgkmcnt(0)
	v_add_f32_e32 v18, v18, v22
	v_fmamk_f32 v18, v18, 0x3a800000, v67
	v_mul_f32_e32 v22, 0x4b800000, v18
	v_cmp_gt_f32_e32 vcc, s19, v18
	s_nop 1
	v_cndmask_b32_e32 v18, v18, v22, vcc
	v_rsq_f32_e32 v18, v18
	s_nop 0
	v_mul_f32_e32 v22, 0x45800000, v18
	v_cndmask_b32_e32 v57, v18, v22, vcc
	s_and_saveexec_b64 s[16:17], s[2:3]
	s_cbranch_execz .LBB0_1074
	v_lshl_add_u64 v[82:83], v[54:55], 3, s[14:15]
	global_store_dwordx2 v[82:83], v[56:57], off
; DEVI void ln_row(float (&x)[16], const float* __restrict__ g, const float* __restrict__ b, int lane, float* mu_out = nullptr,
;                  float* rstd_out = nullptr) {
;     ...
; #pragma unroll
;   for (int i = 0; i < 4; ++i) {
;     float4 gg = *reinterpret_cast<const float4*>(g + i * 256 + lane * 4);
;     float4 bb = *reinterpret_cast<const float4*>(b + i * 256 + lane * 4);
;     x[i * 4 + 0] = (x[i * 4 + 0] - mu) * rstd * gg.x + bb.x;
;     x[i * 4 + 1] = (x[i * 4 + 1] - mu) * rstd * gg.y + bb.y;
;     x[i * 4 + 2] = (x[i * 4 + 2] - mu) * rstd * gg.z + bb.z;
;     x[i * 4 + 3] = (x[i * 4 + 3] - mu) * rstd * gg.w + bb.w;
;   }
; DEVI void ph_lnrouter(const Params& p, int layer, char* shm) {
;     ...
;     float le[16];
; #pragma unroll
;     for (int e = 0; e < 16; ++e) {
;       float a0 = 0.f;
; #pragma unroll
;       for (int i = 0; i < 4; ++i) {
;         float4 wv = *reinterpret_cast<const float4*>(Wt + e * 1024 + i * 256 + lane * 4);
;         a0 += x[i * 4] * wv.x + x[i * 4 + 1] * wv.y + x[i * 4 + 2] * wv.z + x[i * 4 + 3] * wv.w;
;       }
;       le[e] = a0;
;     }
.LBB0_1074:
	s_or_b64 exec, exec, s[16:17]
	v_mul_f32_e32 v18, v80, v57
	s_waitcnt vmcnt(5)
	v_fma_f32 v18, v40, v18, v0
	v_mul_f32_e32 v0, v79, v57
	v_fma_f32 v22, v41, v0, v1
	v_mul_f32_e32 v1, v27, v57
	v_mul_f32_e32 v0, v78, v57
	v_fmac_f32_e32 v3, v43, v1
	v_mul_f32_e32 v1, v77, v57
	v_fma_f32 v0, v42, v0, v2
	s_waitcnt vmcnt(4)
	v_fma_f32 v2, v36, v1, v4
	v_mul_f32_e32 v1, v76, v57
	v_fma_f32 v4, v37, v1, v5
	v_mul_f32_e32 v5, v23, v57
	v_mul_f32_e32 v1, v75, v57
	v_fmac_f32_e32 v7, v39, v5
	v_mul_f32_e32 v5, v26, v57
	v_fma_f32 v1, v38, v1, v6
	s_waitcnt vmcnt(1)
	v_fma_f32 v6, v32, v5, v8
	v_mul_f32_e32 v5, v25, v57
	v_fma_f32 v8, v33, v5, v9
	v_mul_f32_e32 v5, v24, v57
	ds_read_b128 v[24:27], v58
	v_mul_f32_e32 v9, v19, v57
	v_fma_f32 v5, v34, v5, v10
	v_fmac_f32_e32 v11, v35, v9
	v_mul_f32_e32 v9, v20, v57
	v_mul_f32_e32 v10, v21, v57
	s_waitcnt vmcnt(0)
	v_fma_f32 v9, v28, v9, v12
	v_fma_f32 v10, v29, v10, v13
	v_mul_f32_e32 v12, v16, v57
	v_mul_f32_e32 v13, v17, v57
	v_fma_f32 v12, v30, v12, v14
	v_fmac_f32_e32 v15, v13, v31
	ds_read_b128 v[28:31], v58 offset:1024
	s_waitcnt lgkmcnt(1)
	v_mul_f32_e32 v13, v22, v25
	v_fmac_f32_e32 v13, v18, v24
	v_fmac_f32_e32 v13, v0, v26
	v_fmac_f32_e32 v13, v3, v27
	ds_read_b128 v[24:27], v58 offset:2048
	s_waitcnt lgkmcnt(1)
	v_mul_f32_e32 v14, v4, v29
	v_fmac_f32_e32 v14, v2, v28
	v_fmac_f32_e32 v14, v1, v30
	v_add_f32_e32 v13, 0, v13
	v_fmac_f32_e32 v14, v7, v31
	ds_read_b128 v[28:31], v58 offset:3072
	v_add_f32_e32 v13, v13, v14
	s_waitcnt lgkmcnt(1)
	v_mul_f32_e32 v14, v8, v25
	v_fmac_f32_e32 v14, v6, v24
	v_fmac_f32_e32 v14, v5, v26
	v_fmac_f32_e32 v14, v11, v27
	ds_read_b128 v[24:27], v58 offset:4096
	v_add_f32_e32 v13, v13, v14
	s_waitcnt lgkmcnt(1)
	v_mul_f32_e32 v14, v10, v29
	v_fmac_f32_e32 v14, v9, v28
	v_fmac_f32_e32 v14, v12, v30
	v_fmac_f32_e32 v14, v15, v31
	ds_read_b128 v[28:31], v58 offset:5120
	v_add_f32_e32 v13, v13, v14
	s_waitcnt lgkmcnt(1)
	v_mul_f32_e32 v14, v22, v25
	v_fmac_f32_e32 v14, v18, v24
	v_fmac_f32_e32 v14, v0, v26
	v_fmac_f32_e32 v14, v3, v27
	ds_read_b128 v[24:27], v58 offset:6144
	s_waitcnt lgkmcnt(1)
	v_mul_f32_e32 v16, v4, v29
	v_fmac_f32_e32 v16, v2, v28
	v_fmac_f32_e32 v16, v1, v30
	v_add_f32_e32 v14, 0, v14
	v_fmac_f32_e32 v16, v7, v31
	ds_read_b128 v[28:31], v58 offset:7168
	v_add_f32_e32 v14, v14, v16
	s_waitcnt lgkmcnt(1)
	v_mul_f32_e32 v16, v8, v25
	v_fmac_f32_e32 v16, v6, v24
	v_fmac_f32_e32 v16, v5, v26
	v_fmac_f32_e32 v16, v11, v27
	ds_read_b128 v[24:27], v58 offset:8192
	v_add_f32_e32 v14, v14, v16
	s_waitcnt lgkmcnt(1)
	v_mul_f32_e32 v16, v10, v29
	v_fmac_f32_e32 v16, v9, v28
	v_fmac_f32_e32 v16, v12, v30
	v_fmac_f32_e32 v16, v15, v31
	ds_read_b128 v[28:31], v58 offset:9216
	v_add_f32_e32 v14, v14, v16
	s_waitcnt lgkmcnt(1)
	v_mul_f32_e32 v16, v22, v25
	v_fmac_f32_e32 v16, v18, v24
	v_fmac_f32_e32 v16, v0, v26
	v_fmac_f32_e32 v16, v3, v27
	ds_read_b128 v[24:27], v58 offset:10240
	s_waitcnt lgkmcnt(1)
	v_mul_f32_e32 v17, v4, v29
	v_fmac_f32_e32 v17, v2, v28
	v_fmac_f32_e32 v17, v1, v30
	v_add_f32_e32 v16, 0, v16
	v_fmac_f32_e32 v17, v7, v31
	ds_read_b128 v[28:31], v58 offset:11264
	v_add_f32_e32 v16, v16, v17
	s_waitcnt lgkmcnt(1)
	v_mul_f32_e32 v17, v8, v25
	v_fmac_f32_e32 v17, v6, v24
	v_fmac_f32_e32 v17, v5, v26
	v_fmac_f32_e32 v17, v11, v27
	ds_read_b128 v[24:27], v58 offset:12288
	v_add_f32_e32 v16, v16, v17
	s_waitcnt lgkmcnt(1)
	v_mul_f32_e32 v17, v10, v29
	v_fmac_f32_e32 v17, v9, v28
	v_fmac_f32_e32 v17, v12, v30
	v_fmac_f32_e32 v17, v15, v31
	ds_read_b128 v[28:31], v58 offset:13312
	v_add_f32_e32 v16, v16, v17
	s_waitcnt lgkmcnt(1)
	v_mul_f32_e32 v17, v22, v25
	v_fmac_f32_e32 v17, v18, v24
	v_fmac_f32_e32 v17, v0, v26
	v_fmac_f32_e32 v17, v3, v27
	ds_read_b128 v[24:27], v58 offset:14336
	s_waitcnt lgkmcnt(1)
	v_mul_f32_e32 v19, v4, v29
	v_fmac_f32_e32 v19, v2, v28
	v_fmac_f32_e32 v19, v1, v30
	v_add_f32_e32 v17, 0, v17
	v_fmac_f32_e32 v19, v7, v31
	ds_read_b128 v[28:31], v58 offset:15360
	v_add_f32_e32 v17, v17, v19
	s_waitcnt lgkmcnt(1)
	v_mul_f32_e32 v19, v8, v25
	v_fmac_f32_e32 v19, v6, v24
	v_fmac_f32_e32 v19, v5, v26
	v_fmac_f32_e32 v19, v11, v27
	ds_read_b128 v[24:27], v58 offset:16384
	v_add_f32_e32 v17, v17, v19
	s_waitcnt lgkmcnt(1)
	v_mul_f32_e32 v19, v10, v29
	v_fmac_f32_e32 v19, v9, v28
	v_fmac_f32_e32 v19, v12, v30
	v_fmac_f32_e32 v19, v15, v31
	ds_read_b128 v[28:31], v58 offset:17408
	v_add_f32_e32 v17, v17, v19
	s_waitcnt lgkmcnt(1)
	v_mul_f32_e32 v19, v22, v25
	v_fmac_f32_e32 v19, v18, v24
	v_fmac_f32_e32 v19, v0, v26
	v_fmac_f32_e32 v19, v3, v27
	ds_read_b128 v[24:27], v58 offset:18432
	s_waitcnt lgkmcnt(1)
	v_mul_f32_e32 v20, v4, v29
	v_fmac_f32_e32 v20, v2, v28
	v_fmac_f32_e32 v20, v1, v30
	v_add_f32_e32 v19, 0, v19
	v_fmac_f32_e32 v20, v7, v31
	ds_read_b128 v[28:31], v58 offset:19456
	v_add_f32_e32 v19, v19, v20
	s_waitcnt lgkmcnt(1)
	v_mul_f32_e32 v20, v8, v25
	v_fmac_f32_e32 v20, v6, v24
	v_fmac_f32_e32 v20, v5, v26
	v_fmac_f32_e32 v20, v11, v27
	ds_read_b128 v[24:27], v58 offset:20480
	v_add_f32_e32 v19, v19, v20
	s_waitcnt lgkmcnt(1)
	v_mul_f32_e32 v20, v10, v29
	v_fmac_f32_e32 v20, v9, v28
	v_fmac_f32_e32 v20, v12, v30
	v_fmac_f32_e32 v20, v15, v31
	ds_read_b128 v[28:31], v58 offset:21504
	v_add_f32_e32 v19, v19, v20
	s_waitcnt lgkmcnt(1)
	v_mul_f32_e32 v20, v22, v25
	v_fmac_f32_e32 v20, v18, v24
	v_fmac_f32_e32 v20, v0, v26
	v_fmac_f32_e32 v20, v3, v27
	ds_read_b128 v[24:27], v58 offset:22528
	s_waitcnt lgkmcnt(1)
	v_mul_f32_e32 v21, v4, v29
	v_fmac_f32_e32 v21, v2, v28
	v_fmac_f32_e32 v21, v1, v30
	v_add_f32_e32 v20, 0, v20
	v_fmac_f32_e32 v21, v7, v31
	ds_read_b128 v[28:31], v58 offset:23552
	v_add_f32_e32 v20, v20, v21
	s_waitcnt lgkmcnt(1)
; DEVI void ph_lnrouter(const Params& p, int layer, char* shm) {
;     ...
;     float le[16];
; #pragma unroll
;     for (int e = 0; e < 16; ++e) {
;       float a0 = 0.f;
; #pragma unroll
;       for (int i = 0; i < 4; ++i) {
;         float4 wv = *reinterpret_cast<const float4*>(Wt + e * 1024 + i * 256 + lane * 4);
;         a0 += x[i * 4] * wv.x + x[i * 4 + 1] * wv.y + x[i * 4 + 2] * wv.z + x[i * 4 + 3] * wv.w;
;       }
;       le[e] = a0;
;     }
	v_mul_f32_e32 v21, v8, v25
	v_fmac_f32_e32 v21, v6, v24
	v_fmac_f32_e32 v21, v5, v26
	v_fmac_f32_e32 v21, v11, v27
	ds_read_b128 v[24:27], v58 offset:24576
	v_add_f32_e32 v20, v20, v21
	s_waitcnt lgkmcnt(1)
	v_mul_f32_e32 v21, v10, v29
	v_fmac_f32_e32 v21, v9, v28
	v_fmac_f32_e32 v21, v12, v30
	v_fmac_f32_e32 v21, v15, v31
	ds_read_b128 v[28:31], v58 offset:25600
	v_add_f32_e32 v20, v20, v21
	s_waitcnt lgkmcnt(1)
	v_mul_f32_e32 v21, v22, v25
	v_fmac_f32_e32 v21, v18, v24
	v_fmac_f32_e32 v21, v0, v26
	v_fmac_f32_e32 v21, v3, v27
	ds_read_b128 v[24:27], v58 offset:26624
	s_waitcnt lgkmcnt(1)
	v_mul_f32_e32 v23, v4, v29
	v_fmac_f32_e32 v23, v2, v28
	v_fmac_f32_e32 v23, v1, v30
	v_add_f32_e32 v21, 0, v21
	v_fmac_f32_e32 v23, v7, v31
	ds_read_b128 v[28:31], v58 offset:27648
	v_add_f32_e32 v21, v21, v23
	s_waitcnt lgkmcnt(1)
	v_mul_f32_e32 v23, v8, v25
	v_fmac_f32_e32 v23, v6, v24
	v_fmac_f32_e32 v23, v5, v26
	v_fmac_f32_e32 v23, v11, v27
	v_add_f32_e32 v21, v21, v23
	s_waitcnt lgkmcnt(0)
	v_mul_f32_e32 v23, v10, v29
	ds_read_b128 v[24:27], v58 offset:28672
	v_fmac_f32_e32 v23, v9, v28
	v_fmac_f32_e32 v23, v12, v30
	v_fmac_f32_e32 v23, v15, v31
	ds_read_b128 v[28:31], v58 offset:29696
	v_add_f32_e32 v21, v21, v23
	s_waitcnt lgkmcnt(1)
	v_mul_f32_e32 v23, v22, v25
	v_fmac_f32_e32 v23, v18, v24
	v_fmac_f32_e32 v23, v0, v26
	v_fmac_f32_e32 v23, v3, v27
	s_waitcnt lgkmcnt(0)
	v_mul_f32_e32 v29, v4, v29
	ds_read_b128 v[24:27], v58 offset:30720
	v_fmac_f32_e32 v29, v2, v28
	v_fmac_f32_e32 v29, v1, v30
	v_add_f32_e32 v23, 0, v23
	v_fmac_f32_e32 v29, v7, v31
	v_add_f32_e32 v23, v23, v29
	ds_read_b128 v[28:31], v58 offset:31744
	s_waitcnt lgkmcnt(1)
	v_mul_f32_e32 v25, v8, v25
	v_fmac_f32_e32 v25, v6, v24
	v_fmac_f32_e32 v25, v5, v26
	v_fmac_f32_e32 v25, v11, v27
	v_add_f32_e32 v23, v23, v25
	s_waitcnt lgkmcnt(0)
	v_mul_f32_e32 v29, v10, v29
	ds_read_b128 v[24:27], v58 offset:32768
	v_fmac_f32_e32 v29, v9, v28
	v_fmac_f32_e32 v29, v12, v30
	v_fmac_f32_e32 v29, v15, v31
	v_add_f32_e32 v23, v23, v29
	ds_read_b128 v[28:31], v58 offset:33792
	s_waitcnt lgkmcnt(1)
	v_mul_f32_e32 v25, v22, v25
	v_fmac_f32_e32 v25, v18, v24
	v_fmac_f32_e32 v25, v0, v26
	v_fmac_f32_e32 v25, v3, v27
	v_add_f32_e32 v32, 0, v25
	s_waitcnt lgkmcnt(0)
	v_mul_f32_e32 v29, v4, v29
	ds_read_b128 v[24:27], v58 offset:34816
	v_fmac_f32_e32 v29, v2, v28
	v_fmac_f32_e32 v29, v1, v30
	v_fmac_f32_e32 v29, v7, v31
	v_add_f32_e32 v32, v32, v29
	ds_read_b128 v[28:31], v58 offset:35840
	s_waitcnt lgkmcnt(1)
	v_mul_f32_e32 v25, v8, v25
	v_fmac_f32_e32 v25, v6, v24
	v_fmac_f32_e32 v25, v5, v26
	v_fmac_f32_e32 v25, v11, v27
	v_add_f32_e32 v32, v32, v25
	s_waitcnt lgkmcnt(0)
	v_mul_f32_e32 v29, v10, v29
	ds_read_b128 v[24:27], v58 offset:36864
	v_fmac_f32_e32 v29, v9, v28
	v_fmac_f32_e32 v29, v12, v30
	v_fmac_f32_e32 v29, v15, v31
	v_add_f32_e32 v32, v32, v29
	ds_read_b128 v[28:31], v58 offset:37888
	s_waitcnt lgkmcnt(1)
	v_mul_f32_e32 v25, v22, v25
	v_fmac_f32_e32 v25, v18, v24
	v_fmac_f32_e32 v25, v0, v26
	v_fmac_f32_e32 v25, v3, v27
	v_add_f32_e32 v33, 0, v25
	s_waitcnt lgkmcnt(0)
	v_mul_f32_e32 v29, v4, v29
	ds_read_b128 v[24:27], v58 offset:38912
	v_fmac_f32_e32 v29, v2, v28
	v_fmac_f32_e32 v29, v1, v30
	v_fmac_f32_e32 v29, v7, v31
	v_add_f32_e32 v33, v33, v29
	ds_read_b128 v[28:31], v58 offset:39936
	s_waitcnt lgkmcnt(1)
	v_mul_f32_e32 v25, v8, v25
	v_fmac_f32_e32 v25, v6, v24
	v_fmac_f32_e32 v25, v5, v26
	v_fmac_f32_e32 v25, v11, v27
	v_add_f32_e32 v33, v33, v25
	s_waitcnt lgkmcnt(0)
	v_mul_f32_e32 v29, v10, v29
	ds_read_b128 v[24:27], v58 offset:40960
	v_fmac_f32_e32 v29, v9, v28
	v_fmac_f32_e32 v29, v12, v30
	v_fmac_f32_e32 v29, v15, v31
	v_add_f32_e32 v33, v33, v29
	ds_read_b128 v[28:31], v58 offset:41984
	s_waitcnt lgkmcnt(1)
	v_mul_f32_e32 v25, v22, v25
	v_fmac_f32_e32 v25, v18, v24
	v_fmac_f32_e32 v25, v0, v26
	v_fmac_f32_e32 v25, v3, v27
	v_add_f32_e32 v34, 0, v25
	s_waitcnt lgkmcnt(0)
	v_mul_f32_e32 v29, v4, v29
	ds_read_b128 v[24:27], v58 offset:43008
	v_fmac_f32_e32 v29, v2, v28
	v_fmac_f32_e32 v29, v1, v30
	v_fmac_f32_e32 v29, v7, v31
	v_add_f32_e32 v34, v34, v29
	ds_read_b128 v[28:31], v58 offset:44032
	s_waitcnt lgkmcnt(1)
	v_mul_f32_e32 v25, v8, v25
	v_fmac_f32_e32 v25, v6, v24
	v_fmac_f32_e32 v25, v5, v26
	v_fmac_f32_e32 v25, v11, v27
	v_add_f32_e32 v34, v34, v25
	s_waitcnt lgkmcnt(0)
	v_mul_f32_e32 v29, v10, v29
	ds_read_b128 v[24:27], v58 offset:45056
	v_fmac_f32_e32 v29, v9, v28
	v_fmac_f32_e32 v29, v12, v30
	v_fmac_f32_e32 v29, v15, v31
	v_add_f32_e32 v34, v34, v29
	ds_read_b128 v[28:31], v58 offset:46080
	s_waitcnt lgkmcnt(1)
	v_mul_f32_e32 v25, v22, v25
	v_fmac_f32_e32 v25, v18, v24
	v_fmac_f32_e32 v25, v0, v26
	v_fmac_f32_e32 v25, v3, v27
	v_add_f32_e32 v35, 0, v25
	s_waitcnt lgkmcnt(0)
	v_mul_f32_e32 v29, v4, v29
	ds_read_b128 v[24:27], v58 offset:47104
	v_fmac_f32_e32 v29, v2, v28
	v_fmac_f32_e32 v29, v1, v30
	v_fmac_f32_e32 v29, v7, v31
	v_add_f32_e32 v35, v35, v29
	ds_read_b128 v[28:31], v58 offset:48128
	s_waitcnt lgkmcnt(1)
	v_mul_f32_e32 v25, v8, v25
	v_fmac_f32_e32 v25, v6, v24
	v_fmac_f32_e32 v25, v5, v26
	v_fmac_f32_e32 v25, v11, v27
	v_add_f32_e32 v35, v35, v25
	s_waitcnt lgkmcnt(0)
	v_mul_f32_e32 v29, v10, v29
	ds_read_b128 v[24:27], v58 offset:49152
	v_fmac_f32_e32 v29, v9, v28
	v_fmac_f32_e32 v29, v12, v30
	v_fmac_f32_e32 v29, v15, v31
	v_add_f32_e32 v35, v35, v29
	ds_read_b128 v[28:31], v58 offset:50176
	s_waitcnt lgkmcnt(1)
	v_mul_f32_e32 v25, v22, v25
	v_fmac_f32_e32 v25, v18, v24
	v_fmac_f32_e32 v25, v0, v26
	v_fmac_f32_e32 v25, v3, v27
	v_add_f32_e32 v36, 0, v25
	s_waitcnt lgkmcnt(0)
; DEVI float reduce16(float (&v)[16], int lane) {
;   {
;     bool up = (lane & 32) != 0;
; #pragma unroll
;     for (int k = 0; k < 8; ++k) {
;       float send = up ? v[k] : v[k + 8];
;       float keep = up ? v[k + 8] : v[k];
;       v[k] = keep + __shfl_xor(send, 32);
;     }
;   }
; DEVI void ph_lnrouter(const Params& p, int layer, char* shm) {
;     ...
;     float le[16];
; #pragma unroll
;     for (int e = 0; e < 16; ++e) {
;       float a0 = 0.f;
; #pragma unroll
;       for (int i = 0; i < 4; ++i) {
;         float4 wv = *reinterpret_cast<const float4*>(Wt + e * 1024 + i * 256 + lane * 4);
;         a0 += x[i * 4] * wv.x + x[i * 4 + 1] * wv.y + x[i * 4 + 2] * wv.z + x[i * 4 + 3] * wv.w;
;       }
;       le[e] = a0;
;     }
	v_mul_f32_e32 v29, v4, v29
	ds_read_b128 v[24:27], v58 offset:51200
	v_fmac_f32_e32 v29, v2, v28
	v_fmac_f32_e32 v29, v1, v30
	v_fmac_f32_e32 v29, v7, v31
	v_add_f32_e32 v36, v36, v29
	ds_read_b128 v[28:31], v58 offset:52224
	s_waitcnt lgkmcnt(1)
	v_mul_f32_e32 v25, v8, v25
	v_fmac_f32_e32 v25, v6, v24
	v_fmac_f32_e32 v25, v5, v26
	v_fmac_f32_e32 v25, v11, v27
	v_add_f32_e32 v36, v36, v25
	s_waitcnt lgkmcnt(0)
	v_mul_f32_e32 v29, v10, v29
	ds_read_b128 v[24:27], v58 offset:53248
	v_fmac_f32_e32 v29, v9, v28
	v_fmac_f32_e32 v29, v12, v30
	v_fmac_f32_e32 v29, v15, v31
	v_add_f32_e32 v36, v36, v29
	ds_read_b128 v[28:31], v58 offset:54272
	s_waitcnt lgkmcnt(1)
	v_mul_f32_e32 v25, v22, v25
	v_fmac_f32_e32 v25, v18, v24
	v_fmac_f32_e32 v25, v0, v26
	v_fmac_f32_e32 v25, v3, v27
	v_add_f32_e32 v37, 0, v25
	s_waitcnt lgkmcnt(0)
	v_mul_f32_e32 v29, v4, v29
	ds_read_b128 v[24:27], v58 offset:55296
	v_fmac_f32_e32 v29, v2, v28
	v_fmac_f32_e32 v29, v1, v30
	v_fmac_f32_e32 v29, v7, v31
	v_add_f32_e32 v37, v37, v29
	ds_read_b128 v[28:31], v58 offset:56320
	s_waitcnt lgkmcnt(1)
	v_mul_f32_e32 v25, v8, v25
	v_fmac_f32_e32 v25, v6, v24
	v_fmac_f32_e32 v25, v5, v26
	v_fmac_f32_e32 v25, v11, v27
	v_add_f32_e32 v37, v37, v25
	s_waitcnt lgkmcnt(0)
	v_mul_f32_e32 v29, v10, v29
	ds_read_b128 v[24:27], v58 offset:57344
	v_fmac_f32_e32 v29, v9, v28
	v_fmac_f32_e32 v29, v12, v30
	v_fmac_f32_e32 v29, v15, v31
	v_add_f32_e32 v37, v37, v29
	ds_read_b128 v[28:31], v58 offset:58368
	s_waitcnt lgkmcnt(1)
	v_mul_f32_e32 v25, v22, v25
	v_fmac_f32_e32 v25, v18, v24
	v_fmac_f32_e32 v25, v0, v26
	v_fmac_f32_e32 v25, v3, v27
	v_add_f32_e32 v38, 0, v25
	s_waitcnt lgkmcnt(0)
	v_mul_f32_e32 v29, v4, v29
	ds_read_b128 v[24:27], v58 offset:59392
	v_fmac_f32_e32 v29, v2, v28
	v_fmac_f32_e32 v29, v1, v30
	v_fmac_f32_e32 v29, v7, v31
	v_add_f32_e32 v38, v38, v29
	ds_read_b128 v[28:31], v58 offset:60416
	s_waitcnt lgkmcnt(1)
	v_mul_f32_e32 v25, v8, v25
	v_fmac_f32_e32 v25, v6, v24
	v_fmac_f32_e32 v25, v5, v26
	v_fmac_f32_e32 v25, v11, v27
	v_add_f32_e32 v38, v38, v25
	s_waitcnt lgkmcnt(0)
	v_mul_f32_e32 v29, v10, v29
	ds_read_b128 v[24:27], v58 offset:61440
	v_fmac_f32_e32 v29, v9, v28
	v_fmac_f32_e32 v29, v12, v30
	v_fmac_f32_e32 v29, v15, v31
	v_add_f32_e32 v38, v38, v29
	ds_read_b128 v[28:31], v58 offset:62464
	s_waitcnt lgkmcnt(1)
	v_mul_f32_e32 v25, v22, v25
	v_fmac_f32_e32 v25, v18, v24
	v_fmac_f32_e32 v25, v0, v26
	v_fmac_f32_e32 v25, v3, v27
	v_add_f32_e32 v39, 0, v25
	s_waitcnt lgkmcnt(0)
	v_mul_f32_e32 v29, v4, v29
	ds_read_b128 v[24:27], v58 offset:63488
	v_fmac_f32_e32 v29, v2, v28
	v_fmac_f32_e32 v29, v1, v30
	v_fmac_f32_e32 v29, v7, v31
	v_add_f32_e32 v39, v39, v29
	ds_read_b128 v[28:31], v58 offset:64512
	s_waitcnt lgkmcnt(1)
	v_mul_f32_e32 v25, v8, v25
	v_fmac_f32_e32 v25, v6, v24
	v_fmac_f32_e32 v25, v5, v26
	v_fmac_f32_e32 v25, v11, v27
	v_add_f32_e32 v24, v39, v25
	s_waitcnt lgkmcnt(0)
	v_mul_f32_e32 v25, v10, v29
	v_fmac_f32_e32 v25, v9, v28
	v_fmac_f32_e32 v25, v12, v30
	v_fmac_f32_e32 v25, v15, v31
	v_add_f32_e32 v24, v24, v25
	v_cndmask_b32_e64 v25, v13, v32, s[4:5]
	v_cndmask_b32_e64 v26, v14, v33, s[4:5]
	ds_bpermute_b32 v25, v69, v25
	ds_bpermute_b32 v26, v69, v26
	v_cndmask_b32_e64 v13, v32, v13, s[4:5]
	v_cndmask_b32_e64 v14, v33, v14, s[4:5]
	v_cndmask_b32_e64 v27, v16, v34, s[4:5]
	s_waitcnt lgkmcnt(1)
	v_add_f32_e32 v13, v13, v25
	s_waitcnt lgkmcnt(0)
	v_add_f32_e32 v14, v14, v26
	v_cndmask_b32_e64 v25, v17, v35, s[4:5]
	v_cndmask_b32_e64 v26, v19, v36, s[4:5]
	ds_bpermute_b32 v27, v69, v27
	ds_bpermute_b32 v25, v69, v25
	ds_bpermute_b32 v26, v69, v26
	v_cndmask_b32_e64 v16, v34, v16, s[4:5]
	v_cndmask_b32_e64 v17, v35, v17, s[4:5]
	v_cndmask_b32_e64 v19, v36, v19, s[4:5]
	s_waitcnt lgkmcnt(2)
	v_add_f32_e32 v16, v16, v27
	v_cndmask_b32_e64 v27, v20, v37, s[4:5]
	s_waitcnt lgkmcnt(1)
	v_add_f32_e32 v17, v17, v25
	s_waitcnt lgkmcnt(0)
	v_add_f32_e32 v19, v19, v26
	v_cndmask_b32_e64 v25, v21, v38, s[4:5]
	v_cndmask_b32_e64 v26, v23, v24, s[4:5]
	ds_bpermute_b32 v27, v69, v27
	ds_bpermute_b32 v25, v69, v25
	ds_bpermute_b32 v26, v69, v26
	v_cndmask_b32_e64 v20, v37, v20, s[4:5]
	v_cndmask_b32_e64 v21, v38, v21, s[4:5]
	v_cndmask_b32_e64 v23, v24, v23, s[4:5]
	s_waitcnt lgkmcnt(2)
; DEVI float reduce16(float (&v)[16], int lane) {
;     ...
;   {
;     bool up = (lane & 16) != 0;
; #pragma unroll
;     for (int k = 0; k < 4; ++k) {
;       float send = up ? v[k] : v[k + 4];
;       float keep = up ? v[k + 4] : v[k];
;       v[k] = keep + __shfl_xor(send, 16);
;     }
;   }
;   {
;     bool up = (lane & 8) != 0;
; #pragma unroll
;     for (int k = 0; k < 2; ++k) {
;       float send = up ? v[k] : v[k + 2];
;       float keep = up ? v[k + 2] : v[k];
;       v[k] = keep + __shfl_xor(send, 8);
;     }
;   }
;   {
;     bool up = (lane & 4) != 0;
;     float send = up ? v[0] : v[1];
;     float keep = up ? v[1] : v[0];
;     v[0] = keep + __shfl_xor(send, 4);
;   }
;   float r = v[0];
;   r += __shfl_xor(r, 2);
;   r += __shfl_xor(r, 1);
;   return r;
; DEVI void ph_lnrouter(const Params& p, int layer, char* shm) {
;     ...
;       float v = reduce16(le, lane);
;       float mx = v;
;       mx = fmaxf(mx, __shfl_xor(mx, 32));
;       mx = fmaxf(mx, __shfl_xor(mx, 16));
;       mx = fmaxf(mx, __shfl_xor(mx, 8));
;       mx = fmaxf(mx, __shfl_xor(mx, 4));
;       float ex = expf(v - mx);
;       float sm = ex;
;       sm += __shfl_xor(sm, 32);
;       sm += __shfl_xor(sm, 16);
;       sm += __shfl_xor(sm, 8);
;       sm += __shfl_xor(sm, 4);
;       int e = ((lane >> 5) & 1) * 8 + ((lane >> 4) & 1) * 4 + ((lane >> 3) & 1) * 2 + ((lane >> 2) & 1);
;       if ((lane & 3) == 0) aff[(size_t)tok * 16 + e] = ex / sm;
	v_add_f32_e32 v20, v20, v27
	s_waitcnt lgkmcnt(1)
	v_add_f32_e32 v21, v21, v25
	s_waitcnt lgkmcnt(0)
	v_add_f32_e32 v23, v23, v26
	v_cndmask_b32_e64 v27, v13, v19, s[6:7]
	v_cndmask_b32_e64 v13, v19, v13, s[6:7]
	v_cndmask_b32_e64 v19, v14, v20, s[6:7]
	v_cndmask_b32_e64 v14, v20, v14, s[6:7]
	v_cndmask_b32_e64 v20, v16, v21, s[6:7]
	v_cndmask_b32_e64 v24, v17, v23, s[6:7]
	ds_bpermute_b32 v27, v71, v27
	ds_bpermute_b32 v19, v71, v19
	ds_bpermute_b32 v20, v71, v20
	ds_bpermute_b32 v24, v71, v24
	v_cndmask_b32_e64 v16, v21, v16, s[6:7]
	v_cndmask_b32_e64 v17, v23, v17, s[6:7]
	s_waitcnt lgkmcnt(3)
	v_add_f32_e32 v13, v13, v27
	s_waitcnt lgkmcnt(2)
	v_add_f32_e32 v14, v14, v19
	s_waitcnt lgkmcnt(1)
	v_add_f32_e32 v16, v16, v20
	s_waitcnt lgkmcnt(0)
	v_add_f32_e32 v17, v17, v24
	v_cndmask_b32_e64 v19, v13, v16, s[8:9]
	v_cndmask_b32_e64 v20, v14, v17, s[8:9]
	s_nop 1
	v_mov_b32_dpp v19, v19 row_ror:8 row_mask:0xf bank_mask:0xf
	s_nop 1
	v_mov_b32_dpp v20, v20 row_ror:8 row_mask:0xf bank_mask:0xf
	v_cndmask_b32_e64 v13, v16, v13, s[8:9]
	v_cndmask_b32_e64 v14, v17, v14, s[8:9]
	s_waitcnt lgkmcnt(0)
	v_add_f32_e32 v13, v13, v19
	s_waitcnt lgkmcnt(0)
	v_add_f32_e32 v14, v14, v20
	v_cndmask_b32_e64 v16, v13, v14, s[10:11]
	ds_bpermute_b32 v16, v72, v16
	v_cndmask_b32_e64 v13, v14, v13, s[10:11]
	s_waitcnt lgkmcnt(0)
	v_add_f32_e32 v13, v13, v16
	s_nop 1
	v_mov_b32_dpp v14, v13 quad_perm:[2,3,0,1] row_mask:0xf bank_mask:0xf
	s_waitcnt lgkmcnt(0)
	v_add_f32_e32 v13, v13, v14
	s_nop 1
	v_mov_b32_dpp v14, v13 quad_perm:[1,0,3,2] row_mask:0xf bank_mask:0xf
	s_waitcnt lgkmcnt(0)
	v_add_f32_e32 v13, v13, v14
	ds_bpermute_b32 v14, v69, v13
	s_waitcnt lgkmcnt(0)
	v_max_f32_e32 v14, v14, v14
	v_max_f32_e32 v14, v13, v14
	ds_bpermute_b32 v16, v71, v14
	s_waitcnt lgkmcnt(0)
	v_max_f32_e32 v16, v16, v16
	v_max_f32_e32 v14, v14, v16
	s_nop 1
	v_mov_b32_dpp v16, v14 row_ror:8 row_mask:0xf bank_mask:0xf
	s_waitcnt lgkmcnt(0)
	v_max_f32_e32 v16, v16, v16
	v_max_f32_e32 v14, v14, v16
	ds_bpermute_b32 v16, v72, v14
	s_waitcnt lgkmcnt(0)
	v_max_f32_e32 v16, v16, v16
	v_max_f32_e32 v14, v14, v16
	v_sub_f32_e32 v13, v13, v14
	v_mul_f32_e32 v14, 0x3fb8aa3b, v13
	v_fma_f32 v16, v13, s20, -v14
	v_rndne_f32_e32 v17, v14
	v_fmac_f32_e32 v16, 0x32a5705f, v13
	v_sub_f32_e32 v14, v14, v17
	v_add_f32_e32 v14, v14, v16
	v_exp_f32_e32 v14, v14
	v_cvt_i32_f32_e32 v19, v17
	v_cmp_ngt_f32_e32 vcc, s21, v13
	v_lshlrev_b64 v[16:17], 10, v[54:55]
	v_lshl_add_u64 v[16:17], v[50:51], 0, v[16:17]
	v_ldexp_f32 v14, v14, v19
	v_cndmask_b32_e32 v14, 0, v14, vcc
	v_cmp_nlt_f32_e32 vcc, s22, v13
	v_mov_b32_e32 v19, 0
	v_cvt_pk_fp8_f32 v19, v18, v22
	v_cndmask_b32_e32 v13, v68, v14, vcc
	ds_bpermute_b32 v14, v69, v13
	v_mov_b32_e32 v18, 0
	v_cvt_pk_fp8_f32 v18, v2, v4
	v_cvt_pk_fp8_f32 v19, v0, v3 op_sel:[0,0,1]
	s_waitcnt lgkmcnt(0)
	v_add_f32_e32 v2, v13, v14
	ds_bpermute_b32 v4, v71, v2
	v_mov_b32_e32 v14, 0
	v_cvt_pk_fp8_f32 v14, v6, v8
	v_mov_b32_e32 v6, 0
	v_cvt_pk_fp8_f32 v6, v9, v10
	s_waitcnt lgkmcnt(0)
	v_add_f32_e32 v2, v2, v4
	s_nop 1
	v_mov_b32_dpp v4, v2 row_ror:8 row_mask:0xf bank_mask:0xf
	v_cvt_pk_fp8_f32 v18, v1, v7 op_sel:[0,0,1]
	v_cvt_pk_fp8_f32 v14, v5, v11 op_sel:[0,0,1]
	v_cvt_pk_fp8_f32 v6, v12, v15 op_sel:[0,0,1]
	global_store_dword v[16:17], v19, off
	global_store_dword v[16:17], v18, off offset:256
	global_store_dword v[16:17], v14, off offset:512
	global_store_dword v[16:17], v6, off offset:768
	s_waitcnt lgkmcnt(0)
	v_add_f32_e32 v0, v2, v4
	ds_bpermute_b32 v1, v72, v0
	s_and_saveexec_b64 s[16:17], s[12:13]
	s_cbranch_execz .LBB0_1071
	s_waitcnt lgkmcnt(0)
	v_add_f32_e32 v0, v0, v1
	v_div_scale_f32 v1, s[24:25], v0, v0, v13
	v_rcp_f32_e32 v2, v1
	v_div_scale_f32 v3, vcc, v13, v0, v13
	v_fma_f32 v4, -v1, v2, 1.0
	v_fmac_f32_e32 v2, v4, v2
	v_mul_f32_e32 v4, v3, v2
	v_fma_f32 v5, -v1, v4, v3
	v_fmac_f32_e32 v4, v5, v2
	v_fma_f32 v1, -v1, v4, v3
	v_div_fmas_f32 v1, v1, v2, v4
	v_div_fixup_f32 v2, v1, v0, v13
	v_lshlrev_b64 v[0:1], 6, v[54:55]
	v_lshl_add_u64 v[0:1], v[52:53], 0, v[0:1]
	global_store_dword v[0:1], v2, off
	s_branch .LBB0_1071

; DEVI void ln_row(float (&x)[16], const float* __restrict__ g, const float* __restrict__ b, int lane, float* mu_out = nullptr,
;                  float* rstd_out = nullptr) {
;   float s = 0.f;
; #pragma unroll
;   for (int i = 0; i < 16; ++i) s += x[i];
;   s = wave_sum(s);
;   float mu = s * (1.0f / 1024.0f);
;   float v = 0.f;
; #pragma unroll
;   for (int i = 0; i < 16; ++i) { float d = x[i] - mu; v += d * d; }
;   v = wave_sum(v);
;   float rstd = rsqrtf(v * (1.0f / 1024.0f) + 1e-5f);
;   if (mu_out) { *mu_out = mu; *rstd_out = rstd; }
; DEVI void ph_lnrouter(const Params& p, int layer, char* shm) {
;     ...
;     const int tok = it * 8 + w;
;     float x[16];
; #pragma unroll
;     for (int i = 0; i < 4; ++i) {
;       float4 v = *reinterpret_cast<const float4*>(h32 + (size_t)tok * 1024 + i * 256 + lane * 4);
;       x[i * 4] = v.x; x[i * 4 + 1] = v.y; x[i * 4 + 2] = v.z; x[i * 4 + 3] = v.w;
;     }
;     float mu_, rstd_;
;     ln_row(x, g, b, lane, &mu_, &rstd_);
;     if (lane == 0) ((float2*)(p.ws + OFF_HB))[tok] = make_float2(mu_, rstd_);
.LBB0_1908:
	v_ashrrev_i32_e32 v55, 31, v54
	s_waitcnt lgkmcnt(0)
	v_lshlrev_b64 v[0:1], 12, v[54:55]
	v_lshl_add_u64 v[0:1], v[44:45], 0, v[0:1]
	global_load_dwordx4 v[24:27], v[0:1], off
	global_load_dwordx4 v[20:23], v[0:1], off offset:1024
	global_load_dwordx4 v[16:19], v[0:1], off offset:2048
	global_load_dwordx4 v[82:85], v[0:1], off offset:3072
	v_cmp_lt_i32_e32 vcc, v61, v60
	s_nop 1
	v_cndmask_b32_e32 v0, v59, v61, vcc
	v_lshlrev_b32_e32 v69, 2, v0
	v_cmp_lt_i32_e32 vcc, v62, v60
	s_waitcnt vmcnt(3)
	v_add_f32_e32 v0, 0, v24
	v_add_f32_e32 v0, v25, v0
	v_add_f32_e32 v0, v26, v0
	v_add_f32_e32 v0, v27, v0
	s_waitcnt vmcnt(2)
	v_add_f32_e32 v0, v20, v0
	v_add_f32_e32 v0, v21, v0
	v_add_f32_e32 v0, v22, v0
	v_add_f32_e32 v0, v23, v0
	s_waitcnt vmcnt(1)
	v_add_f32_e32 v0, v16, v0
	v_add_f32_e32 v0, v17, v0
	v_add_f32_e32 v0, v18, v0
	v_add_f32_e32 v0, v19, v0
	s_waitcnt vmcnt(0)
	v_add_f32_e32 v0, v82, v0
	v_add_f32_e32 v0, v83, v0
	v_add_f32_e32 v0, v84, v0
	v_add_f32_e32 v0, v85, v0
	ds_bpermute_b32 v1, v69, v0
	v_cndmask_b32_e32 v2, v59, v62, vcc
	v_lshlrev_b32_e32 v71, 2, v2
	v_cmp_lt_i32_e32 vcc, v63, v60
	s_waitcnt lgkmcnt(0)
	v_add_f32_e32 v0, v0, v1
	ds_bpermute_b32 v1, v71, v0
	v_cndmask_b32_e32 v2, v59, v63, vcc
	v_lshlrev_b32_e32 v70, 2, v2
	v_cmp_lt_i32_e32 vcc, v64, v60
	s_waitcnt lgkmcnt(0)
	v_add_f32_e32 v0, v0, v1
	s_nop 1
	v_mov_b32_dpp v1, v0 row_ror:8 row_mask:0xf bank_mask:0xf
	v_cndmask_b32_e32 v2, v59, v64, vcc
	v_lshlrev_b32_e32 v72, 2, v2
	v_cmp_lt_i32_e32 vcc, v65, v60
	s_waitcnt lgkmcnt(0)
	v_add_f32_e32 v0, v0, v1
	ds_bpermute_b32 v1, v72, v0
	v_cndmask_b32_e32 v3, v59, v65, vcc
	v_lshlrev_b32_e32 v74, 2, v3
	v_cmp_lt_i32_e32 vcc, v66, v60
	s_waitcnt lgkmcnt(0)
	v_add_f32_e32 v8, v0, v1
	s_nop 1
	v_mov_b32_dpp v9, v8 quad_perm:[2,3,0,1] row_mask:0xf bank_mask:0xf
	v_cndmask_b32_e32 v2, v59, v66, vcc
	v_lshlrev_b32_e32 v73, 2, v2
	global_load_dwordx4 v[40:43], v[46:47], off
	global_load_dwordx4 v[36:39], v[46:47], off offset:1024
	global_load_dwordx4 v[0:3], v[48:49], off
	global_load_dwordx4 v[4:7], v[48:49], off offset:1024
	s_waitcnt lgkmcnt(0)
	v_add_f32_e32 v56, v8, v9
	global_load_dwordx4 v[32:35], v[46:47], off offset:2048
	global_load_dwordx4 v[28:31], v[46:47], off offset:3072
	global_load_dwordx4 v[8:11], v[48:49], off offset:2048
	global_load_dwordx4 v[12:15], v[48:49], off offset:3072
	s_nop 1
	v_mov_b32_dpp v57, v56 quad_perm:[1,0,3,2] row_mask:0xf bank_mask:0xf
	s_waitcnt lgkmcnt(0)
	v_add_f32_e32 v57, v56, v57
	v_fmamk_f32 v79, v57, 0xba800000, v25
	v_fmamk_f32 v80, v57, 0xba800000, v24
	v_fmamk_f32 v24, v57, 0xba800000, v18
	v_mul_f32_e32 v18, v79, v79
	v_fmamk_f32 v78, v57, 0xba800000, v26
	v_fmac_f32_e32 v18, v80, v80
	v_fmac_f32_e32 v27, 0xba800000, v57
	v_fmac_f32_e32 v18, v78, v78
	v_fmamk_f32 v77, v57, 0xba800000, v20
	v_fmac_f32_e32 v18, v27, v27
	v_fmamk_f32 v76, v57, 0xba800000, v21
	v_fmac_f32_e32 v18, v77, v77
	v_fmamk_f32 v75, v57, 0xba800000, v22
	v_fmac_f32_e32 v18, v76, v76
	v_fmac_f32_e32 v23, 0xba800000, v57
	v_fmac_f32_e32 v18, v75, v75
	v_fmamk_f32 v26, v57, 0xba800000, v16
	v_fmac_f32_e32 v18, v23, v23
	v_fmamk_f32 v25, v57, 0xba800000, v17
	v_fmac_f32_e32 v18, v26, v26
	v_mul_f32_e32 v56, 0x3a800000, v57
	v_fmac_f32_e32 v18, v25, v25
	v_fmac_f32_e32 v19, 0xba800000, v57
	v_pk_add_f32 v[20:21], v[82:83], v[56:57] op_sel_hi:[1,0] neg_lo:[0,1] neg_hi:[0,1]
	v_fmac_f32_e32 v18, v24, v24
	v_pk_mul_f32 v[82:83], v[20:21], v[20:21]
	v_fmac_f32_e32 v18, v19, v19
	v_pk_add_f32 v[16:17], v[84:85], v[56:57] op_sel_hi:[1,0] neg_lo:[0,1] neg_hi:[0,1]
	v_add_f32_e32 v18, v82, v18
	v_pk_mul_f32 v[84:85], v[16:17], v[16:17]
	v_add_f32_e32 v18, v83, v18
	v_add_f32_e32 v18, v84, v18
	v_add_f32_e32 v18, v85, v18
	ds_bpermute_b32 v22, v69, v18
	s_waitcnt lgkmcnt(0)
	v_add_f32_e32 v18, v18, v22
	ds_bpermute_b32 v22, v71, v18
	s_waitcnt lgkmcnt(0)
	v_add_f32_e32 v18, v18, v22
	s_nop 1
	v_mov_b32_dpp v22, v18 row_ror:8 row_mask:0xf bank_mask:0xf
	s_waitcnt lgkmcnt(0)
	v_add_f32_e32 v18, v18, v22
	ds_bpermute_b32 v22, v72, v18
	s_waitcnt lgkmcnt(0)
	v_add_f32_e32 v18, v18, v22
	s_nop 1
	v_mov_b32_dpp v22, v18 quad_perm:[2,3,0,1] row_mask:0xf bank_mask:0xf
	s_waitcnt lgkmcnt(0)
	v_add_f32_e32 v18, v18, v22
	s_nop 1
	v_mov_b32_dpp v22, v18 quad_perm:[1,0,3,2] row_mask:0xf bank_mask:0xf
	s_waitcnt lgkmcnt(0)
	v_add_f32_e32 v18, v18, v22
	v_fmamk_f32 v18, v18, 0x3a800000, v67
	v_mul_f32_e32 v22, 0x4b800000, v18
	v_cmp_gt_f32_e32 vcc, s5, v18
	s_nop 1
	v_cndmask_b32_e32 v18, v18, v22, vcc
	v_rsq_f32_e32 v18, v18
	s_nop 0
	v_mul_f32_e32 v22, 0x45800000, v18
	v_cndmask_b32_e32 v57, v18, v22, vcc
	s_and_saveexec_b64 s[2:3], s[6:7]
	s_cbranch_execz .LBB0_1910
	v_lshl_add_u64 v[82:83], v[54:55], 3, s[0:1]
	global_store_dwordx2 v[82:83], v[56:57], off
; DEVI void ln_row(float (&x)[16], const float* __restrict__ g, const float* __restrict__ b, int lane, float* mu_out = nullptr,
;                  float* rstd_out = nullptr) {
;     ...
; #pragma unroll
;   for (int i = 0; i < 4; ++i) {
;     float4 gg = *reinterpret_cast<const float4*>(g + i * 256 + lane * 4);
;     float4 bb = *reinterpret_cast<const float4*>(b + i * 256 + lane * 4);
;     x[i * 4 + 0] = (x[i * 4 + 0] - mu) * rstd * gg.x + bb.x;
;     x[i * 4 + 1] = (x[i * 4 + 1] - mu) * rstd * gg.y + bb.y;
;     x[i * 4 + 2] = (x[i * 4 + 2] - mu) * rstd * gg.z + bb.z;
;     x[i * 4 + 3] = (x[i * 4 + 3] - mu) * rstd * gg.w + bb.w;
;   }
; DEVI void ph_lnrouter(const Params& p, int layer, char* shm) {
;     ...
;     float le[16];
; #pragma unroll
;     for (int e = 0; e < 16; ++e) {
;       float a0 = 0.f;
; #pragma unroll
;       for (int i = 0; i < 4; ++i) {
;         float4 wv = *reinterpret_cast<const float4*>(Wt + e * 1024 + i * 256 + lane * 4);
;         a0 += x[i * 4] * wv.x + x[i * 4 + 1] * wv.y + x[i * 4 + 2] * wv.z + x[i * 4 + 3] * wv.w;
;       }
;       le[e] = a0;
;     }
.LBB0_1910:
	s_or_b64 exec, exec, s[2:3]
	v_mul_f32_e32 v18, v80, v57
	s_waitcnt vmcnt(5)
	v_fma_f32 v18, v40, v18, v0
	v_mul_f32_e32 v0, v79, v57
	v_fma_f32 v22, v41, v0, v1
	v_mul_f32_e32 v1, v27, v57
	v_mul_f32_e32 v0, v78, v57
	v_fmac_f32_e32 v3, v43, v1
	v_mul_f32_e32 v1, v77, v57
	v_fma_f32 v0, v42, v0, v2
	s_waitcnt vmcnt(4)
	v_fma_f32 v2, v36, v1, v4
	v_mul_f32_e32 v1, v76, v57
	v_fma_f32 v4, v37, v1, v5
	v_mul_f32_e32 v5, v23, v57
	v_mul_f32_e32 v1, v75, v57
	v_fmac_f32_e32 v7, v39, v5
	v_mul_f32_e32 v5, v26, v57
	v_fma_f32 v1, v38, v1, v6
	s_waitcnt vmcnt(1)
	v_fma_f32 v6, v32, v5, v8
	v_mul_f32_e32 v5, v25, v57
	v_fma_f32 v8, v33, v5, v9
	v_mul_f32_e32 v5, v24, v57
	ds_read_b128 v[24:27], v58
	v_mul_f32_e32 v9, v19, v57
	v_fma_f32 v5, v34, v5, v10
	v_fmac_f32_e32 v11, v35, v9
	v_mul_f32_e32 v9, v20, v57
	v_mul_f32_e32 v10, v21, v57
	s_waitcnt vmcnt(0)
	v_fma_f32 v9, v28, v9, v12
	v_fma_f32 v10, v29, v10, v13
	v_mul_f32_e32 v12, v16, v57
	v_mul_f32_e32 v13, v17, v57
	v_fma_f32 v12, v30, v12, v14
	v_fmac_f32_e32 v15, v13, v31
	ds_read_b128 v[28:31], v58 offset:1024
	s_waitcnt lgkmcnt(1)
	v_mul_f32_e32 v13, v22, v25
	v_fmac_f32_e32 v13, v18, v24
	v_fmac_f32_e32 v13, v0, v26
	v_fmac_f32_e32 v13, v3, v27
	ds_read_b128 v[24:27], v58 offset:2048
	s_waitcnt lgkmcnt(1)
	v_mul_f32_e32 v14, v4, v29
	v_fmac_f32_e32 v14, v2, v28
	v_fmac_f32_e32 v14, v1, v30
	v_add_f32_e32 v13, 0, v13
	v_fmac_f32_e32 v14, v7, v31
	ds_read_b128 v[28:31], v58 offset:3072
	v_add_f32_e32 v13, v13, v14
	s_waitcnt lgkmcnt(1)
	v_mul_f32_e32 v14, v8, v25
	v_fmac_f32_e32 v14, v6, v24
	v_fmac_f32_e32 v14, v5, v26
	v_fmac_f32_e32 v14, v11, v27
	ds_read_b128 v[24:27], v58 offset:4096
	v_add_f32_e32 v13, v13, v14
	s_waitcnt lgkmcnt(1)
	v_mul_f32_e32 v14, v10, v29
	v_fmac_f32_e32 v14, v9, v28
	v_fmac_f32_e32 v14, v12, v30
	v_fmac_f32_e32 v14, v15, v31
	ds_read_b128 v[28:31], v58 offset:5120
	v_add_f32_e32 v13, v13, v14
	s_waitcnt lgkmcnt(1)
	v_mul_f32_e32 v14, v22, v25
	v_fmac_f32_e32 v14, v18, v24
	v_fmac_f32_e32 v14, v0, v26
	v_fmac_f32_e32 v14, v3, v27
	ds_read_b128 v[24:27], v58 offset:6144
	s_waitcnt lgkmcnt(1)
	v_mul_f32_e32 v16, v4, v29
	v_fmac_f32_e32 v16, v2, v28
	v_fmac_f32_e32 v16, v1, v30
	v_add_f32_e32 v14, 0, v14
	v_fmac_f32_e32 v16, v7, v31
	ds_read_b128 v[28:31], v58 offset:7168
	v_add_f32_e32 v14, v14, v16
	s_waitcnt lgkmcnt(1)
	v_mul_f32_e32 v16, v8, v25
	v_fmac_f32_e32 v16, v6, v24
	v_fmac_f32_e32 v16, v5, v26
	v_fmac_f32_e32 v16, v11, v27
	ds_read_b128 v[24:27], v58 offset:8192
	v_add_f32_e32 v14, v14, v16
	s_waitcnt lgkmcnt(1)
	v_mul_f32_e32 v16, v10, v29
	v_fmac_f32_e32 v16, v9, v28
	v_fmac_f32_e32 v16, v12, v30
	v_fmac_f32_e32 v16, v15, v31
	ds_read_b128 v[28:31], v58 offset:9216
	v_add_f32_e32 v14, v14, v16
	s_waitcnt lgkmcnt(1)
	v_mul_f32_e32 v16, v22, v25
	v_fmac_f32_e32 v16, v18, v24
	v_fmac_f32_e32 v16, v0, v26
	v_fmac_f32_e32 v16, v3, v27
	ds_read_b128 v[24:27], v58 offset:10240
	s_waitcnt lgkmcnt(1)
	v_mul_f32_e32 v17, v4, v29
	v_fmac_f32_e32 v17, v2, v28
	v_fmac_f32_e32 v17, v1, v30
	v_add_f32_e32 v16, 0, v16
	v_fmac_f32_e32 v17, v7, v31
	ds_read_b128 v[28:31], v58 offset:11264
	v_add_f32_e32 v16, v16, v17
	s_waitcnt lgkmcnt(1)
	v_mul_f32_e32 v17, v8, v25
	v_fmac_f32_e32 v17, v6, v24
	v_fmac_f32_e32 v17, v5, v26
	v_fmac_f32_e32 v17, v11, v27
	ds_read_b128 v[24:27], v58 offset:12288
	v_add_f32_e32 v16, v16, v17
	s_waitcnt lgkmcnt(1)
	v_mul_f32_e32 v17, v10, v29
	v_fmac_f32_e32 v17, v9, v28
	v_fmac_f32_e32 v17, v12, v30
	v_fmac_f32_e32 v17, v15, v31
	ds_read_b128 v[28:31], v58 offset:13312
	v_add_f32_e32 v16, v16, v17
	s_waitcnt lgkmcnt(1)
	v_mul_f32_e32 v17, v22, v25
	v_fmac_f32_e32 v17, v18, v24
	v_fmac_f32_e32 v17, v0, v26
	v_fmac_f32_e32 v17, v3, v27
	ds_read_b128 v[24:27], v58 offset:14336
	s_waitcnt lgkmcnt(1)
	v_mul_f32_e32 v19, v4, v29
	v_fmac_f32_e32 v19, v2, v28
	v_fmac_f32_e32 v19, v1, v30
	v_add_f32_e32 v17, 0, v17
	v_fmac_f32_e32 v19, v7, v31
	ds_read_b128 v[28:31], v58 offset:15360
	v_add_f32_e32 v17, v17, v19
	s_waitcnt lgkmcnt(1)
	v_mul_f32_e32 v19, v8, v25
	v_fmac_f32_e32 v19, v6, v24
	v_fmac_f32_e32 v19, v5, v26
	v_fmac_f32_e32 v19, v11, v27
	ds_read_b128 v[24:27], v58 offset:16384
	v_add_f32_e32 v17, v17, v19
	s_waitcnt lgkmcnt(1)
	v_mul_f32_e32 v19, v10, v29
	v_fmac_f32_e32 v19, v9, v28
	v_fmac_f32_e32 v19, v12, v30
	v_fmac_f32_e32 v19, v15, v31
	ds_read_b128 v[28:31], v58 offset:17408
	v_add_f32_e32 v17, v17, v19
	s_waitcnt lgkmcnt(1)
	v_mul_f32_e32 v19, v22, v25
	v_fmac_f32_e32 v19, v18, v24
	v_fmac_f32_e32 v19, v0, v26
	v_fmac_f32_e32 v19, v3, v27
	ds_read_b128 v[24:27], v58 offset:18432
	s_waitcnt lgkmcnt(1)
	v_mul_f32_e32 v20, v4, v29
	v_fmac_f32_e32 v20, v2, v28
	v_fmac_f32_e32 v20, v1, v30
	v_add_f32_e32 v19, 0, v19
	v_fmac_f32_e32 v20, v7, v31
	ds_read_b128 v[28:31], v58 offset:19456
	v_add_f32_e32 v19, v19, v20
	s_waitcnt lgkmcnt(1)
	v_mul_f32_e32 v20, v8, v25
	v_fmac_f32_e32 v20, v6, v24
	v_fmac_f32_e32 v20, v5, v26
	v_fmac_f32_e32 v20, v11, v27
	ds_read_b128 v[24:27], v58 offset:20480
	v_add_f32_e32 v19, v19, v20
	s_waitcnt lgkmcnt(1)
	v_mul_f32_e32 v20, v10, v29
	v_fmac_f32_e32 v20, v9, v28
	v_fmac_f32_e32 v20, v12, v30
	v_fmac_f32_e32 v20, v15, v31
	ds_read_b128 v[28:31], v58 offset:21504
	v_add_f32_e32 v19, v19, v20
	s_waitcnt lgkmcnt(1)
	v_mul_f32_e32 v20, v22, v25
	v_fmac_f32_e32 v20, v18, v24
	v_fmac_f32_e32 v20, v0, v26
	v_fmac_f32_e32 v20, v3, v27
	ds_read_b128 v[24:27], v58 offset:22528
	s_waitcnt lgkmcnt(1)
	v_mul_f32_e32 v21, v4, v29
	v_fmac_f32_e32 v21, v2, v28
	v_fmac_f32_e32 v21, v1, v30
	v_add_f32_e32 v20, 0, v20
	v_fmac_f32_e32 v21, v7, v31
	ds_read_b128 v[28:31], v58 offset:23552
	v_add_f32_e32 v20, v20, v21
	s_waitcnt lgkmcnt(1)
; DEVI void ph_lnrouter(const Params& p, int layer, char* shm) {
;     ...
;     float le[16];
; #pragma unroll
;     for (int e = 0; e < 16; ++e) {
;       float a0 = 0.f;
; #pragma unroll
;       for (int i = 0; i < 4; ++i) {
;         float4 wv = *reinterpret_cast<const float4*>(Wt + e * 1024 + i * 256 + lane * 4);
;         a0 += x[i * 4] * wv.x + x[i * 4 + 1] * wv.y + x[i * 4 + 2] * wv.z + x[i * 4 + 3] * wv.w;
;       }
;       le[e] = a0;
;     }
	v_mul_f32_e32 v21, v8, v25
	v_fmac_f32_e32 v21, v6, v24
	v_fmac_f32_e32 v21, v5, v26
	v_fmac_f32_e32 v21, v11, v27
	ds_read_b128 v[24:27], v58 offset:24576
	v_add_f32_e32 v20, v20, v21
	s_waitcnt lgkmcnt(1)
	v_mul_f32_e32 v21, v10, v29
	v_fmac_f32_e32 v21, v9, v28
	v_fmac_f32_e32 v21, v12, v30
	v_fmac_f32_e32 v21, v15, v31
	ds_read_b128 v[28:31], v58 offset:25600
	v_add_f32_e32 v20, v20, v21
	s_waitcnt lgkmcnt(1)
	v_mul_f32_e32 v21, v22, v25
	v_fmac_f32_e32 v21, v18, v24
	v_fmac_f32_e32 v21, v0, v26
	v_fmac_f32_e32 v21, v3, v27
	ds_read_b128 v[24:27], v58 offset:26624
	s_waitcnt lgkmcnt(1)
	v_mul_f32_e32 v23, v4, v29
	v_fmac_f32_e32 v23, v2, v28
	v_fmac_f32_e32 v23, v1, v30
	v_add_f32_e32 v21, 0, v21
	v_fmac_f32_e32 v23, v7, v31
	ds_read_b128 v[28:31], v58 offset:27648
	v_add_f32_e32 v21, v21, v23
	s_waitcnt lgkmcnt(1)
	v_mul_f32_e32 v23, v8, v25
	v_fmac_f32_e32 v23, v6, v24
	v_fmac_f32_e32 v23, v5, v26
	v_fmac_f32_e32 v23, v11, v27
	v_add_f32_e32 v21, v21, v23
	s_waitcnt lgkmcnt(0)
	v_mul_f32_e32 v23, v10, v29
	ds_read_b128 v[24:27], v58 offset:28672
	v_fmac_f32_e32 v23, v9, v28
	v_fmac_f32_e32 v23, v12, v30
	v_fmac_f32_e32 v23, v15, v31
	ds_read_b128 v[28:31], v58 offset:29696
	v_add_f32_e32 v21, v21, v23
	s_waitcnt lgkmcnt(1)
	v_mul_f32_e32 v23, v22, v25
	v_fmac_f32_e32 v23, v18, v24
	v_fmac_f32_e32 v23, v0, v26
	v_fmac_f32_e32 v23, v3, v27
	s_waitcnt lgkmcnt(0)
	v_mul_f32_e32 v29, v4, v29
	ds_read_b128 v[24:27], v58 offset:30720
	v_fmac_f32_e32 v29, v2, v28
	v_fmac_f32_e32 v29, v1, v30
	v_add_f32_e32 v23, 0, v23
	v_fmac_f32_e32 v29, v7, v31
	v_add_f32_e32 v23, v23, v29
	ds_read_b128 v[28:31], v58 offset:31744
	s_waitcnt lgkmcnt(1)
	v_mul_f32_e32 v25, v8, v25
	v_fmac_f32_e32 v25, v6, v24
	v_fmac_f32_e32 v25, v5, v26
	v_fmac_f32_e32 v25, v11, v27
	v_add_f32_e32 v23, v23, v25
	s_waitcnt lgkmcnt(0)
	v_mul_f32_e32 v29, v10, v29
	ds_read_b128 v[24:27], v58 offset:32768
	v_fmac_f32_e32 v29, v9, v28
	v_fmac_f32_e32 v29, v12, v30
	v_fmac_f32_e32 v29, v15, v31
	v_add_f32_e32 v23, v23, v29
	ds_read_b128 v[28:31], v58 offset:33792
	s_waitcnt lgkmcnt(1)
	v_mul_f32_e32 v25, v22, v25
	v_fmac_f32_e32 v25, v18, v24
	v_fmac_f32_e32 v25, v0, v26
	v_fmac_f32_e32 v25, v3, v27
	v_add_f32_e32 v32, 0, v25
	s_waitcnt lgkmcnt(0)
	v_mul_f32_e32 v29, v4, v29
	ds_read_b128 v[24:27], v58 offset:34816
	v_fmac_f32_e32 v29, v2, v28
	v_fmac_f32_e32 v29, v1, v30
	v_fmac_f32_e32 v29, v7, v31
	v_add_f32_e32 v32, v32, v29
	ds_read_b128 v[28:31], v58 offset:35840
	s_waitcnt lgkmcnt(1)
	v_mul_f32_e32 v25, v8, v25
	v_fmac_f32_e32 v25, v6, v24
	v_fmac_f32_e32 v25, v5, v26
	v_fmac_f32_e32 v25, v11, v27
	v_add_f32_e32 v32, v32, v25
	s_waitcnt lgkmcnt(0)
	v_mul_f32_e32 v29, v10, v29
	ds_read_b128 v[24:27], v58 offset:36864
	v_fmac_f32_e32 v29, v9, v28
	v_fmac_f32_e32 v29, v12, v30
	v_fmac_f32_e32 v29, v15, v31
	v_add_f32_e32 v32, v32, v29
	ds_read_b128 v[28:31], v58 offset:37888
	s_waitcnt lgkmcnt(1)
	v_mul_f32_e32 v25, v22, v25
	v_fmac_f32_e32 v25, v18, v24
	v_fmac_f32_e32 v25, v0, v26
	v_fmac_f32_e32 v25, v3, v27
	v_add_f32_e32 v33, 0, v25
	s_waitcnt lgkmcnt(0)
	v_mul_f32_e32 v29, v4, v29
	ds_read_b128 v[24:27], v58 offset:38912
	v_fmac_f32_e32 v29, v2, v28
	v_fmac_f32_e32 v29, v1, v30
	v_fmac_f32_e32 v29, v7, v31
	v_add_f32_e32 v33, v33, v29
	ds_read_b128 v[28:31], v58 offset:39936
	s_waitcnt lgkmcnt(1)
	v_mul_f32_e32 v25, v8, v25
	v_fmac_f32_e32 v25, v6, v24
	v_fmac_f32_e32 v25, v5, v26
	v_fmac_f32_e32 v25, v11, v27
	v_add_f32_e32 v33, v33, v25
	s_waitcnt lgkmcnt(0)
	v_mul_f32_e32 v29, v10, v29
	ds_read_b128 v[24:27], v58 offset:40960
	v_fmac_f32_e32 v29, v9, v28
	v_fmac_f32_e32 v29, v12, v30
	v_fmac_f32_e32 v29, v15, v31
	v_add_f32_e32 v33, v33, v29
	ds_read_b128 v[28:31], v58 offset:41984
	s_waitcnt lgkmcnt(1)
	v_mul_f32_e32 v25, v22, v25
	v_fmac_f32_e32 v25, v18, v24
	v_fmac_f32_e32 v25, v0, v26
	v_fmac_f32_e32 v25, v3, v27
	v_add_f32_e32 v34, 0, v25
	s_waitcnt lgkmcnt(0)
	v_mul_f32_e32 v29, v4, v29
	ds_read_b128 v[24:27], v58 offset:43008
	v_fmac_f32_e32 v29, v2, v28
	v_fmac_f32_e32 v29, v1, v30
	v_fmac_f32_e32 v29, v7, v31
	v_add_f32_e32 v34, v34, v29
	ds_read_b128 v[28:31], v58 offset:44032
	s_waitcnt lgkmcnt(1)
	v_mul_f32_e32 v25, v8, v25
	v_fmac_f32_e32 v25, v6, v24
	v_fmac_f32_e32 v25, v5, v26
	v_fmac_f32_e32 v25, v11, v27
	v_add_f32_e32 v34, v34, v25
	s_waitcnt lgkmcnt(0)
	v_mul_f32_e32 v29, v10, v29
	ds_read_b128 v[24:27], v58 offset:45056
	v_fmac_f32_e32 v29, v9, v28
	v_fmac_f32_e32 v29, v12, v30
	v_fmac_f32_e32 v29, v15, v31
	v_add_f32_e32 v34, v34, v29
	ds_read_b128 v[28:31], v58 offset:46080
	s_waitcnt lgkmcnt(1)
	v_mul_f32_e32 v25, v22, v25
	v_fmac_f32_e32 v25, v18, v24
	v_fmac_f32_e32 v25, v0, v26
	v_fmac_f32_e32 v25, v3, v27
	v_add_f32_e32 v35, 0, v25
	s_waitcnt lgkmcnt(0)
	v_mul_f32_e32 v29, v4, v29
	ds_read_b128 v[24:27], v58 offset:47104
	v_fmac_f32_e32 v29, v2, v28
	v_fmac_f32_e32 v29, v1, v30
	v_fmac_f32_e32 v29, v7, v31
	v_add_f32_e32 v35, v35, v29
	ds_read_b128 v[28:31], v58 offset:48128
	s_waitcnt lgkmcnt(1)
	v_mul_f32_e32 v25, v8, v25
	v_fmac_f32_e32 v25, v6, v24
	v_fmac_f32_e32 v25, v5, v26
	v_fmac_f32_e32 v25, v11, v27
	v_add_f32_e32 v35, v35, v25
	s_waitcnt lgkmcnt(0)
	v_mul_f32_e32 v29, v10, v29
	ds_read_b128 v[24:27], v58 offset:49152
	v_fmac_f32_e32 v29, v9, v28
	v_fmac_f32_e32 v29, v12, v30
	v_fmac_f32_e32 v29, v15, v31
	v_add_f32_e32 v35, v35, v29
	ds_read_b128 v[28:31], v58 offset:50176
	s_waitcnt lgkmcnt(1)
	v_mul_f32_e32 v25, v22, v25
	v_fmac_f32_e32 v25, v18, v24
	v_fmac_f32_e32 v25, v0, v26
	v_fmac_f32_e32 v25, v3, v27
	v_add_f32_e32 v36, 0, v25
	s_waitcnt lgkmcnt(0)
; DEVI float reduce16(float (&v)[16], int lane) {
;   {
;     bool up = (lane & 32) != 0;
; #pragma unroll
;     for (int k = 0; k < 8; ++k) {
;       float send = up ? v[k] : v[k + 8];
;       float keep = up ? v[k + 8] : v[k];
;       v[k] = keep + __shfl_xor(send, 32);
;     }
;   }
; DEVI void ph_lnrouter(const Params& p, int layer, char* shm) {
;     ...
;     float le[16];
; #pragma unroll
;     for (int e = 0; e < 16; ++e) {
;       float a0 = 0.f;
; #pragma unroll
;       for (int i = 0; i < 4; ++i) {
;         float4 wv = *reinterpret_cast<const float4*>(Wt + e * 1024 + i * 256 + lane * 4);
;         a0 += x[i * 4] * wv.x + x[i * 4 + 1] * wv.y + x[i * 4 + 2] * wv.z + x[i * 4 + 3] * wv.w;
;       }
;       le[e] = a0;
;     }
	v_mul_f32_e32 v29, v4, v29
	ds_read_b128 v[24:27], v58 offset:51200
	v_fmac_f32_e32 v29, v2, v28
	v_fmac_f32_e32 v29, v1, v30
	v_fmac_f32_e32 v29, v7, v31
	v_add_f32_e32 v36, v36, v29
	ds_read_b128 v[28:31], v58 offset:52224
	s_waitcnt lgkmcnt(1)
	v_mul_f32_e32 v25, v8, v25
	v_fmac_f32_e32 v25, v6, v24
	v_fmac_f32_e32 v25, v5, v26
	v_fmac_f32_e32 v25, v11, v27
	v_add_f32_e32 v36, v36, v25
	s_waitcnt lgkmcnt(0)
	v_mul_f32_e32 v29, v10, v29
	ds_read_b128 v[24:27], v58 offset:53248
	v_fmac_f32_e32 v29, v9, v28
	v_fmac_f32_e32 v29, v12, v30
	v_fmac_f32_e32 v29, v15, v31
	v_add_f32_e32 v36, v36, v29
	ds_read_b128 v[28:31], v58 offset:54272
	s_waitcnt lgkmcnt(1)
	v_mul_f32_e32 v25, v22, v25
	v_fmac_f32_e32 v25, v18, v24
	v_fmac_f32_e32 v25, v0, v26
	v_fmac_f32_e32 v25, v3, v27
	v_add_f32_e32 v37, 0, v25
	s_waitcnt lgkmcnt(0)
	v_mul_f32_e32 v29, v4, v29
	ds_read_b128 v[24:27], v58 offset:55296
	v_fmac_f32_e32 v29, v2, v28
	v_fmac_f32_e32 v29, v1, v30
	v_fmac_f32_e32 v29, v7, v31
	v_add_f32_e32 v37, v37, v29
	ds_read_b128 v[28:31], v58 offset:56320
	s_waitcnt lgkmcnt(1)
	v_mul_f32_e32 v25, v8, v25
	v_fmac_f32_e32 v25, v6, v24
	v_fmac_f32_e32 v25, v5, v26
	v_fmac_f32_e32 v25, v11, v27
	v_add_f32_e32 v37, v37, v25
	s_waitcnt lgkmcnt(0)
	v_mul_f32_e32 v29, v10, v29
	ds_read_b128 v[24:27], v58 offset:57344
	v_fmac_f32_e32 v29, v9, v28
	v_fmac_f32_e32 v29, v12, v30
	v_fmac_f32_e32 v29, v15, v31
	v_add_f32_e32 v37, v37, v29
	ds_read_b128 v[28:31], v58 offset:58368
	s_waitcnt lgkmcnt(1)
	v_mul_f32_e32 v25, v22, v25
	v_fmac_f32_e32 v25, v18, v24
	v_fmac_f32_e32 v25, v0, v26
	v_fmac_f32_e32 v25, v3, v27
	v_add_f32_e32 v38, 0, v25
	s_waitcnt lgkmcnt(0)
	v_mul_f32_e32 v29, v4, v29
	ds_read_b128 v[24:27], v58 offset:59392
	v_fmac_f32_e32 v29, v2, v28
	v_fmac_f32_e32 v29, v1, v30
	v_fmac_f32_e32 v29, v7, v31
	v_add_f32_e32 v38, v38, v29
	ds_read_b128 v[28:31], v58 offset:60416
	s_waitcnt lgkmcnt(1)
	v_mul_f32_e32 v25, v8, v25
	v_fmac_f32_e32 v25, v6, v24
	v_fmac_f32_e32 v25, v5, v26
	v_fmac_f32_e32 v25, v11, v27
	v_add_f32_e32 v38, v38, v25
	s_waitcnt lgkmcnt(0)
	v_mul_f32_e32 v29, v10, v29
	ds_read_b128 v[24:27], v58 offset:61440
	v_fmac_f32_e32 v29, v9, v28
	v_fmac_f32_e32 v29, v12, v30
	v_fmac_f32_e32 v29, v15, v31
	v_add_f32_e32 v38, v38, v29
	ds_read_b128 v[28:31], v58 offset:62464
	s_waitcnt lgkmcnt(1)
	v_mul_f32_e32 v25, v22, v25
	v_fmac_f32_e32 v25, v18, v24
	v_fmac_f32_e32 v25, v0, v26
	v_fmac_f32_e32 v25, v3, v27
	v_add_f32_e32 v39, 0, v25
	s_waitcnt lgkmcnt(0)
	v_mul_f32_e32 v29, v4, v29
	ds_read_b128 v[24:27], v58 offset:63488
	v_fmac_f32_e32 v29, v2, v28
	v_fmac_f32_e32 v29, v1, v30
	v_fmac_f32_e32 v29, v7, v31
	v_add_f32_e32 v39, v39, v29
	ds_read_b128 v[28:31], v58 offset:64512
	s_waitcnt lgkmcnt(1)
	v_mul_f32_e32 v25, v8, v25
	v_fmac_f32_e32 v25, v6, v24
	v_fmac_f32_e32 v25, v5, v26
	v_fmac_f32_e32 v25, v11, v27
	v_add_f32_e32 v24, v39, v25
	s_waitcnt lgkmcnt(0)
	v_mul_f32_e32 v25, v10, v29
	v_fmac_f32_e32 v25, v9, v28
	v_fmac_f32_e32 v25, v12, v30
	v_fmac_f32_e32 v25, v15, v31
	v_add_f32_e32 v24, v24, v25
	v_cndmask_b32_e64 v25, v13, v32, s[8:9]
	v_cndmask_b32_e64 v26, v14, v33, s[8:9]
	ds_bpermute_b32 v25, v69, v25
	ds_bpermute_b32 v26, v69, v26
	v_cndmask_b32_e64 v13, v32, v13, s[8:9]
	v_cndmask_b32_e64 v14, v33, v14, s[8:9]
	v_cndmask_b32_e64 v27, v16, v34, s[8:9]
	s_waitcnt lgkmcnt(1)
	v_add_f32_e32 v13, v13, v25
	s_waitcnt lgkmcnt(0)
	v_add_f32_e32 v14, v14, v26
	v_cndmask_b32_e64 v25, v17, v35, s[8:9]
	v_cndmask_b32_e64 v26, v19, v36, s[8:9]
	ds_bpermute_b32 v27, v69, v27
	ds_bpermute_b32 v25, v69, v25
	ds_bpermute_b32 v26, v69, v26
	v_cndmask_b32_e64 v16, v34, v16, s[8:9]
	v_cndmask_b32_e64 v17, v35, v17, s[8:9]
	v_cndmask_b32_e64 v19, v36, v19, s[8:9]
	s_waitcnt lgkmcnt(2)
	v_add_f32_e32 v16, v16, v27
	v_cndmask_b32_e64 v27, v20, v37, s[8:9]
	s_waitcnt lgkmcnt(1)
	v_add_f32_e32 v17, v17, v25
	s_waitcnt lgkmcnt(0)
	v_add_f32_e32 v19, v19, v26
	v_cndmask_b32_e64 v25, v21, v38, s[8:9]
	v_cndmask_b32_e64 v26, v23, v24, s[8:9]
	ds_bpermute_b32 v27, v69, v27
	ds_bpermute_b32 v25, v69, v25
	ds_bpermute_b32 v26, v69, v26
	v_cndmask_b32_e64 v20, v37, v20, s[8:9]
	v_cndmask_b32_e64 v21, v38, v21, s[8:9]
	v_cndmask_b32_e64 v23, v24, v23, s[8:9]
	s_waitcnt lgkmcnt(2)
; DEVI float reduce16(float (&v)[16], int lane) {
;     ...
;   {
;     bool up = (lane & 16) != 0;
; #pragma unroll
;     for (int k = 0; k < 4; ++k) {
;       float send = up ? v[k] : v[k + 4];
;       float keep = up ? v[k + 4] : v[k];
;       v[k] = keep + __shfl_xor(send, 16);
;     }
;   }
;   {
;     bool up = (lane & 8) != 0;
; #pragma unroll
;     for (int k = 0; k < 2; ++k) {
;       float send = up ? v[k] : v[k + 2];
;       float keep = up ? v[k + 2] : v[k];
;       v[k] = keep + __shfl_xor(send, 8);
;     }
;   }
;   {
;     bool up = (lane & 4) != 0;
;     float send = up ? v[0] : v[1];
;     float keep = up ? v[1] : v[0];
;     v[0] = keep + __shfl_xor(send, 4);
;   }
;   float r = v[0];
;   r += __shfl_xor(r, 2);
;   r += __shfl_xor(r, 1);
;   return r;
; DEVI void ph_lnrouter(const Params& p, int layer, char* shm) {
;     ...
;       float v = reduce16(le, lane);
;       float mx = v;
;       mx = fmaxf(mx, __shfl_xor(mx, 32));
;       mx = fmaxf(mx, __shfl_xor(mx, 16));
;       mx = fmaxf(mx, __shfl_xor(mx, 8));
;       mx = fmaxf(mx, __shfl_xor(mx, 4));
;       float ex = expf(v - mx);
;       float sm = ex;
;       sm += __shfl_xor(sm, 32);
;       sm += __shfl_xor(sm, 16);
;       sm += __shfl_xor(sm, 8);
;       sm += __shfl_xor(sm, 4);
;       int e = ((lane >> 5) & 1) * 8 + ((lane >> 4) & 1) * 4 + ((lane >> 3) & 1) * 2 + ((lane >> 2) & 1);
;       if ((lane & 3) == 0) aff[(size_t)tok * 16 + e] = ex / sm;
	v_add_f32_e32 v20, v20, v27
	s_waitcnt lgkmcnt(1)
	v_add_f32_e32 v21, v21, v25
	s_waitcnt lgkmcnt(0)
	v_add_f32_e32 v23, v23, v26
	v_cndmask_b32_e64 v27, v13, v19, s[10:11]
	v_cndmask_b32_e64 v13, v19, v13, s[10:11]
	v_cndmask_b32_e64 v19, v14, v20, s[10:11]
	v_cndmask_b32_e64 v14, v20, v14, s[10:11]
	v_cndmask_b32_e64 v20, v16, v21, s[10:11]
	v_cndmask_b32_e64 v24, v17, v23, s[10:11]
	ds_bpermute_b32 v27, v71, v27
	ds_bpermute_b32 v19, v71, v19
	ds_bpermute_b32 v20, v71, v20
	ds_bpermute_b32 v24, v71, v24
	v_cndmask_b32_e64 v16, v21, v16, s[10:11]
	v_cndmask_b32_e64 v17, v23, v17, s[10:11]
	s_waitcnt lgkmcnt(3)
	v_add_f32_e32 v13, v13, v27
	s_waitcnt lgkmcnt(2)
	v_add_f32_e32 v14, v14, v19
	s_waitcnt lgkmcnt(1)
	v_add_f32_e32 v16, v16, v20
	s_waitcnt lgkmcnt(0)
	v_add_f32_e32 v17, v17, v24
	v_cndmask_b32_e64 v19, v13, v16, s[12:13]
	v_cndmask_b32_e64 v20, v14, v17, s[12:13]
	s_nop 1
	v_mov_b32_dpp v19, v19 row_ror:8 row_mask:0xf bank_mask:0xf
	s_nop 1
	v_mov_b32_dpp v20, v20 row_ror:8 row_mask:0xf bank_mask:0xf
	v_cndmask_b32_e64 v13, v16, v13, s[12:13]
	v_cndmask_b32_e64 v14, v17, v14, s[12:13]
	s_waitcnt lgkmcnt(0)
	v_add_f32_e32 v13, v13, v19
	s_waitcnt lgkmcnt(0)
	v_add_f32_e32 v14, v14, v20
	v_cndmask_b32_e64 v16, v13, v14, s[14:15]
	ds_bpermute_b32 v16, v72, v16
	v_cndmask_b32_e64 v13, v14, v13, s[14:15]
	s_waitcnt lgkmcnt(0)
	v_add_f32_e32 v13, v13, v16
	s_nop 1
	v_mov_b32_dpp v14, v13 quad_perm:[2,3,0,1] row_mask:0xf bank_mask:0xf
	s_waitcnt lgkmcnt(0)
	v_add_f32_e32 v13, v13, v14
	s_nop 1
	v_mov_b32_dpp v14, v13 quad_perm:[1,0,3,2] row_mask:0xf bank_mask:0xf
	s_waitcnt lgkmcnt(0)
	v_add_f32_e32 v13, v13, v14
	ds_bpermute_b32 v14, v69, v13
	s_waitcnt lgkmcnt(0)
	v_max_f32_e32 v14, v14, v14
	v_max_f32_e32 v14, v13, v14
	ds_bpermute_b32 v16, v71, v14
	s_waitcnt lgkmcnt(0)
	v_max_f32_e32 v16, v16, v16
	v_max_f32_e32 v14, v14, v16
	s_nop 1
	v_mov_b32_dpp v16, v14 row_ror:8 row_mask:0xf bank_mask:0xf
	s_waitcnt lgkmcnt(0)
	v_max_f32_e32 v16, v16, v16
	v_max_f32_e32 v14, v14, v16
	ds_bpermute_b32 v16, v72, v14
	s_waitcnt lgkmcnt(0)
	v_max_f32_e32 v16, v16, v16
	v_max_f32_e32 v14, v14, v16
	v_sub_f32_e32 v13, v13, v14
	v_mul_f32_e32 v14, 0x3fb8aa3b, v13
	v_fma_f32 v16, v13, s18, -v14
	v_rndne_f32_e32 v17, v14
	v_fmac_f32_e32 v16, 0x32a5705f, v13
	v_sub_f32_e32 v14, v14, v17
	v_add_f32_e32 v14, v14, v16
	v_exp_f32_e32 v14, v14
	v_cvt_i32_f32_e32 v19, v17
	v_cmp_ngt_f32_e32 vcc, s19, v13
	v_lshlrev_b64 v[16:17], 10, v[54:55]
	v_lshl_add_u64 v[16:17], v[50:51], 0, v[16:17]
	v_ldexp_f32 v14, v14, v19
	v_cndmask_b32_e32 v14, 0, v14, vcc
	v_cmp_nlt_f32_e32 vcc, s20, v13
	v_mov_b32_e32 v19, 0
	v_cvt_pk_fp8_f32 v19, v18, v22
	v_cndmask_b32_e32 v13, v68, v14, vcc
	ds_bpermute_b32 v14, v69, v13
	v_mov_b32_e32 v18, 0
	v_cvt_pk_fp8_f32 v18, v2, v4
	v_cvt_pk_fp8_f32 v19, v0, v3 op_sel:[0,0,1]
	s_waitcnt lgkmcnt(0)
	v_add_f32_e32 v2, v13, v14
	ds_bpermute_b32 v4, v71, v2
	v_mov_b32_e32 v14, 0
	v_cvt_pk_fp8_f32 v14, v6, v8
	v_mov_b32_e32 v6, 0
	v_cvt_pk_fp8_f32 v6, v9, v10
	s_waitcnt lgkmcnt(0)
	v_add_f32_e32 v2, v2, v4
	s_nop 1
	v_mov_b32_dpp v4, v2 row_ror:8 row_mask:0xf bank_mask:0xf
	v_cvt_pk_fp8_f32 v18, v1, v7 op_sel:[0,0,1]
	v_cvt_pk_fp8_f32 v14, v5, v11 op_sel:[0,0,1]
	v_cvt_pk_fp8_f32 v6, v12, v15 op_sel:[0,0,1]
	global_store_dword v[16:17], v19, off
	global_store_dword v[16:17], v18, off offset:256
	global_store_dword v[16:17], v14, off offset:512
	global_store_dword v[16:17], v6, off offset:768
	s_waitcnt lgkmcnt(0)
	v_add_f32_e32 v0, v2, v4
	ds_bpermute_b32 v1, v72, v0
	s_and_saveexec_b64 s[2:3], s[16:17]
	s_cbranch_execz .LBB0_1907
	s_waitcnt lgkmcnt(0)
	v_add_f32_e32 v0, v0, v1
	v_div_scale_f32 v1, s[22:23], v0, v0, v13
	v_rcp_f32_e32 v2, v1
	v_div_scale_f32 v3, vcc, v13, v0, v13
	v_fma_f32 v4, -v1, v2, 1.0
	v_fmac_f32_e32 v2, v4, v2
	v_mul_f32_e32 v4, v3, v2
	v_fma_f32 v5, -v1, v4, v3
	v_fmac_f32_e32 v4, v5, v2
	v_fma_f32 v1, -v1, v4, v3
	v_div_fmas_f32 v1, v1, v2, v4
	v_div_fixup_f32 v2, v1, v0, v13
	v_lshlrev_b64 v[0:1], 6, v[54:55]
	v_lshl_add_u64 v[0:1], v[52:53], 0, v[0:1]
	global_store_dword v[0:1], v2, off
	s_branch .LBB0_1907
